# replace the sleep stagger by useful work: XCD group 4-7 runs the (independent) PLE-projection GEMM right after the P3 barrier, group 0-3 keeps it in P7
# speedup vs baseline: 1.0150x; 1.0088x over previous
.LBB0_126:
	s_mov_b32 s99, 0
	s_cmp_lg_u32 s3, 0x100
	s_cbranch_scc1 .Lflag_done
	v_mbcnt_lo_u32_b32 v0, -1, 0
	v_mbcnt_hi_u32_b32 v0, -1, v0
	v_lshlrev_b32_e32 v1, 4, v0
	v_add_u32_e32 v1, 0xe000, v1
	global_load_dwordx4 v[4:7], v1, s[76:77]
	v_and_b32_e32 v2, 1, v0
	s_waitcnt vmcnt(0)
	v_readlane_b32 s4, v4, 0
	v_readlane_b32 s5, v5, 0
	v_readlane_b32 s6, v6, 0
	v_readlane_b32 s7, v7, 0
	v_readlane_b32 s8, v4, 1
	v_readlane_b32 s9, v5, 1
	v_readlane_b32 s10, v6, 1
	v_readlane_b32 s11, v7, 1
	v_cmp_eq_u32_e32 vcc, 1, v2
	v_mov_b32_e32 v8, s4
	v_mov_b32_e32 v9, s8
	v_cndmask_b32_e32 v8, v8, v9, vcc
	v_mov_b32_e32 v10, s5
	v_mov_b32_e32 v9, s9
	v_cndmask_b32_e32 v10, v10, v9, vcc
	v_mov_b32_e32 v11, s6
	v_mov_b32_e32 v9, s10
	v_cndmask_b32_e32 v11, v11, v9, vcc
	v_mov_b32_e32 v12, s7
	v_mov_b32_e32 v9, s11
	v_cndmask_b32_e32 v12, v12, v9, vcc
	v_xor_b32_e32 v8, v4, v8
	v_xor_b32_e32 v10, v5, v10
	v_xor_b32_e32 v11, v6, v11
	v_xor_b32_e32 v12, v7, v12
	v_or3_b32 v8, v8, v10, v11
	v_or_b32_e32 v8, v8, v12
	v_min_u32_e32 v9, v4, v5
	v_min3_u32 v9, v9, v6, v7
	v_cmp_ne_u32_e32 vcc, 0, v8
	v_cmp_eq_u32_e64 s[4:5], 0, v9
	s_nop 3
	s_or_b64 s[4:5], vcc, s[4:5]
	s_cmp_lg_u64 s[4:5], 0
	s_cbranch_scc1 .Lflag_done
	s_mov_b32 s99, 1
	s_bitcmp1_b32 s2, 2
	s_cbranch_scc0 .Lflag_done
	s_or_b32 s99, s99, 16

.LBB0_694:
	s_bitcmp1_b32 s99, 4
	s_cbranch_scc0 .Lp4_go
	v_writelane_b32 v255, s36, 34
	v_writelane_b32 v255, s37, 35
	v_writelane_b32 v255, s38, 36
	v_writelane_b32 v255, s39, 37
	v_writelane_b32 v255, s40, 38
	v_writelane_b32 v255, s41, 39
	s_or_b32 s99, s99, 32
	s_branch .Lpp_entry

.Lpp_entry:
	v_mov_b32_e32 v0, 0
	s_add_u32 s4, s76, 0x16c00000
	v_mbcnt_lo_u32_b32 v0, -1, v0
	s_addc_u32 s5, s77, 0
	v_mbcnt_hi_u32_b32 v0, -1, v0
	s_waitcnt vmcnt(19)
	v_add_u32_e32 v8, s33, v0
	s_cmpk_lt_i32 s2, 0x200
	v_mov_b32_e32 v142, 0
	s_cselect_b64 s[6:7], -1, 0
	s_cmpk_gt_i32 s2, 0x1ff
	v_readfirstlane_b32 s14, v8
	s_cbranch_scc1 .LBB0_1001
	s_bitcmp1_b32 s99, 5
	s_cbranch_scc1 .Lpp_noskip
	s_bitcmp1_b32 s99, 4
	s_cbranch_scc1 .LBB0_1001
.Lpp_noskip:
	s_ashr_i32 s8, s2, 31
	s_lshr_b32 s0, s8, 29
	s_add_i32 s10, s2, s0
	s_and_b32 s0, s10, -8
	s_sub_i32 s11, s2, s0
	s_cmp_gt_i32 s11, -1
	s_cbranch_scc0 .LBB0_982
	s_lshl_b32 s9, s11, 6
	s_cbranch_execz .LBB0_983
	s_branch .LBB0_984

.LBB0_1000:
	s_waitcnt vmcnt(0)
	s_barrier
	s_bitcmp1_b32 s99, 5
	s_cbranch_scc0 .Lpp_noret
	v_readlane_b32 s36, v255, 34
	v_readlane_b32 s37, v255, 35
	v_readlane_b32 s38, v255, 36
	v_readlane_b32 s39, v255, 37
	v_readlane_b32 s40, v255, 38
	v_readlane_b32 s41, v255, 39
	v_readlane_b32 s27, v255, 0
	v_readlane_b32 s54, v255, 1
	v_readlane_b32 s55, v255, 2
	s_andn2_b32 s99, s99, 32
	s_branch .Lp4_go
.Lpp_noret:
.LBB0_1001:
	s_andn2_b64 vcc, exec, s[6:7]
	v_mbcnt_lo_u32_b32 v0, -1, v142
	v_mbcnt_hi_u32_b32 v0, -1, v0
	v_add_u32_e32 v8, s33, v0
	s_nop 0
	v_readfirstlane_b32 s10, v8
	s_cbranch_vccnz .LBB0_1031
	s_ashr_i32 s33, s2, 31
	s_lshr_b32 s0, s33, 29
	s_add_i32 s8, s2, s0
	s_and_b32 s0, s8, -8
	s_sub_i32 s7, s2, s0
	s_cmp_gt_i32 s7, -1
	s_cbranch_scc0 .LBB0_1004
	s_lshl_b32 s6, s7, 6
	s_ashr_i32 s0, s8, 3
	s_cbranch_execz .LBB0_1005
	s_branch .LBB0_1006
